# 3-way rotation of phase +3 sections (conv / prompt attention / sample attention) by unit-index block (vcu>>4)%3, 2-way in phase +5, on top of ST2
# baseline (speedup 1.0000x reference)
; #define SUB(k, bit) (!(kargs()->li == 1 && (k) == lo) || ((kargs()->submask >> (bit)) & 1u))
; __global__ void __launch_bounds__(NWAVES * 64, 2) fwd(Args args_unused) {
;     ...
;         if (IN(pb + 3)) {
;             PH_PTRS PH_LAYER
;             if (SUB(pb + 3, 0)) {
;                 const int nitems = (M / 16) * 5;
; #pragma unroll 1
;                 for (int it = gw; it < nitems; it += NGW) {
;                     const int seg = it / 5, c = (it - seg * 5) * 64 + lane;
;                     if (c >= 192 && seg * 16 < NPROMPT) continue;
.LBB0_1364:
	v_readlane_b32 s99, v254, 3
	s_nop 3
	s_lshr_b32 s99, s99, 4
	s_mul_hi_u32 s98, s99, 0x55555556
	s_mul_i32 s98, s98, 3
	s_sub_u32 s98, s99, s98
	s_mov_b32 s100, 0
.Lro_again_0:
	s_cmp_lt_i32 s84, 7
	s_cselect_b64 s[0:1], -1, 0
	s_cmp_gt_i32 s85, 6
	s_waitcnt lgkmcnt(0)
	s_cselect_b64 s[4:5], -1, 0
	s_and_b64 s[0:1], s[0:1], s[4:5]
	s_andn2_b64 vcc, exec, s[0:1]
	s_cbranch_vccnz .LBB0_1520
	s_mov_b64 s[26:27], s[82:83]
	s_load_dwordx2 s[28:29], s[26:27], 0x148
	s_mov_b32 s62, 0
	s_load_dword s64, s[82:83], 0x168
	v_readlane_b32 s33, v254, 3
	s_mov_b32 s3, s2
	v_mov_b32_e32 v1, v0
	s_waitcnt lgkmcnt(0)
	s_lshl_b32 s4, s33, 3
	v_readfirstlane_b32 s61, v1
	s_ashr_i32 s63, s61, 6
	s_lshl_b32 s3, s64, 3
	s_add_i32 s60, s63, s4
	s_add_u32 s30, s28, 0x1d200000
	s_addc_u32 s31, s29, 0
	s_cmpk_gt_i32 s60, 0x284f
	v_and_b32_e32 v130, 63, v1
	s_cselect_b32 s99, 1, 0
	s_cmp_lg_u32 s100, 0
	s_cbranch_scc1 .Lro_k0_0
	s_cmp_lg_u32 s98, 0
	s_cbranch_scc1 .LBB0_1477
.Lro_k0_0:
	s_cmp_lg_u32 s99, 0
	s_cbranch_scc1 .LBB0_1477
	s_add_u32 s8, s28, 0x4d800000
	s_addc_u32 s9, s29, 0
	s_add_u32 s10, s28, 0x53900000
	s_addc_u32 s11, s29, 0
	s_lshl_b32 s4, s33, 9
	s_lshl_b32 s5, s63, 6
	s_add_i32 s4, s4, s5
	v_or_b32_e32 v131, s4, v130
	v_lshlrev_b32_e32 v140, 3, v131
	s_lshl_b32 s65, s64, 12
	s_lshl_b32 s66, s64, 9
	s_movk_i32 s67, 0xc0
	s_movk_i32 s68, 0xbf
	v_mov_b32_e32 v133, 0
	v_mov_b32_e32 v141, 0x400
	v_mov_b32_e32 v142, 0x600
	v_mov_b32_e32 v143, 0x1c00
	v_mov_b32_e32 v144, 0x1600
	v_mov_b32_e32 v145, 0xd8
	v_mov_b32_e32 v146, 0xa0
	v_mov_b32_e32 v147, 0xe0
	v_mov_b32_e32 v148, 0xa8
	v_mov_b32_e32 v149, 0xc00
	s_mov_b32 s69, s60
	s_branch .LBB0_1368

; #define LAS __attribute__((address_space(3)))
; __global__ void __launch_bounds__(NWAVES * 64, 2) fwd(Args args_unused) {
;     ...
;                 LAS unsigned char* KB0 = lds; LAS unsigned char* VB0 = lds + 65536; LAS float* bsm = (LAS float*)(lds + 131072);
;                 const int qq = lane & 15, q4 = lane >> 4, w = wave;
;                 constexpr int NUN = 16 * 3 * 8 * 16;
;     ...
;                 bf16x8 qn[2] = {(bf16x8){0, 0, 0, 0, 0, 0, 0, 0}, (bf16x8){0, 0, 0, 0, 0, 0, 0, 0}}; float bnx = 0.f;
;                 __syncthreads();
;                 if (vcu < NUN) ATT_ISSUE(vcu, 0, qn);
.LBB0_1477:
	s_cmp_lg_u32 s100, 0
	s_cbranch_scc0 .Lro_a1_0
	s_cmp_eq_u32 s98, 1
	s_cbranch_scc1 .Lro_fin_0
.Lro_a1_0:
	s_add_u32 s34, s28, 0xb800000
	s_addc_u32 s35, s29, 0
	s_add_u32 s36, s28, 0x67c00000
	s_addc_u32 s37, s29, 0
	s_cmpk_lt_i32 s33, 0x1800
	s_waitcnt vmcnt(0)
	s_barrier
	s_cselect_b32 s99, 1, 0
	s_cmp_lg_u32 s100, 0
	s_cbranch_scc1 .Lro_k2_0
	s_cmp_eq_u32 s98, 2
	s_cbranch_scc1 .LBB0_1496
.Lro_k2_0:
	s_cmp_lg_u32 s99, 0
	s_cbranch_scc0 .LBB0_1496
	s_add_i32 s46, s62, 0x10000
	s_add_u32 s38, s28, 0xb000000
	s_addc_u32 s39, s29, 0
	s_ashr_i32 s4, s33, 7
	s_mul_hi_i32 s6, s4, 0x55555556
	s_lshr_b32 s7, s6, 31
	s_add_i32 s6, s6, s7
	s_mul_i32 s6, s6, 3
	s_sub_i32 s9, s4, s6
	s_mul_hi_i32 s4, s33, 0x2aaaaaab
	s_lshr_b32 s6, s4, 31
	s_ashr_i32 s4, s4, 6
	s_and_b32 s5, s33, 15
	s_bfe_u32 s8, s33, 0x30004
	s_add_i32 s4, s4, s6
	s_cmp_eq_u32 s9, 1
	s_cselect_b32 s6, 2, 4
	s_cmp_lg_u32 s9, 0
	s_cselect_b32 s12, s6, 0
	s_sub_i32 s7, 4, s12
	v_lshrrev_b32_e32 v4, 3, v130
	s_lshr_b32 s6, 16, s12
	s_lshr_b32 s13, s5, s7
	v_bitop3_b32 v5, v4, v1, 7 bitop3:0x78
	s_lshl_b32 s10, s9, 9
	s_lshl_b32 s15, s8, 6
	s_mul_i32 s6, s13, s6
	s_or_b32 s16, s10, s15
	v_lshlrev_b32_e32 v29, 3, v5
	s_sub_i32 s5, s5, s6
	v_or_b32_e32 v5, s16, v29
	s_lshl_b32 s14, s5, 7
	v_or_b32_e32 v28, 0xffffff80, v4
	v_add_u32_e32 v4, 0x600, v5
	v_mov_b32_e32 v30, 0xf8
	v_add_u32_e32 v12, s14, v28
	v_lshrrev_b32_e32 v13, 8, v4
	v_bitop3_b32 v4, s16, v30, v29 bitop3:0xc8
	s_lshl_b32 s47, s63, 3
	s_ashr_i32 s5, s4, 31
	v_lshlrev_b32_e32 v6, 1, v4
	v_mov_b32_e32 v4, 0
	v_add_u32_e32 v8, s47, v12
	s_lshl_b64 s[4:5], s[4:5], 11
	v_max_i32_e32 v8, 0, v8
	v_mov_b32_e32 v9, v4
	s_or_b32 s6, s4, s13
	s_mov_b32 s7, s5
	v_lshlrev_b64 v[8:9], s12, v[8:9]
	v_add_u32_e32 v5, 0xc00, v5
	v_lshl_add_u64 v[8:9], s[6:7], 0, v[8:9]
	s_mov_b32 s48, 0x8100
	v_mov_b32_e32 v7, v4
	v_lshrrev_b32_e32 v5, 8, v5
	v_mad_u64_u32 v[10:11], s[10:11], v13, s48, v[8:9]
	v_lshl_add_u64 v[6:7], s[30:31], 0, v[6:7]
	v_lshlrev_b64 v[10:11], 9, v[10:11]
	s_lshl_b32 s49, s63, 10
	v_mad_u64_u32 v[8:9], s[10:11], v5, s48, v[8:9]
	v_lshl_add_u64 v[10:11], v[6:7], 0, v[10:11]
	s_add_i32 m0, s62, s49
	v_lshlrev_b64 v[8:9], 9, v[8:9]
	s_add_i32 s24, s63, 8
	global_load_lds_dwordx4 v[10:11], off
	v_lshl_add_u64 v[8:9], v[6:7], 0, v[8:9]
	s_add_i32 m0, s46, s49
	s_lshl_b32 s50, s24, 3
	global_load_lds_dwordx4 v[8:9], off
	v_add_u32_e32 v8, s50, v12
	v_max_i32_e32 v8, 0, v8
	v_mov_b32_e32 v9, v4
	v_lshlrev_b64 v[8:9], s12, v[8:9]
	v_lshl_add_u64 v[8:9], s[6:7], 0, v[8:9]
	v_mad_u64_u32 v[10:11], s[10:11], v13, s48, v[8:9]
	v_lshlrev_b64 v[10:11], 9, v[10:11]
	s_lshl_b32 s51, s24, 10
	v_mad_u64_u32 v[8:9], s[10:11], v5, s48, v[8:9]
	v_lshl_add_u64 v[10:11], v[6:7], 0, v[10:11]
	s_add_i32 m0, s62, s51
	v_lshlrev_b64 v[8:9], 9, v[8:9]
	s_add_i32 s17, s63, 16
	global_load_lds_dwordx4 v[10:11], off
	v_lshl_add_u64 v[8:9], v[6:7], 0, v[8:9]
	s_add_i32 m0, s46, s51
	s_lshl_b32 s52, s17, 3
	global_load_lds_dwordx4 v[8:9], off
	v_add_u32_e32 v8, s52, v12
	v_max_i32_e32 v8, 0, v8
	v_mov_b32_e32 v9, v4
	v_lshlrev_b64 v[8:9], s12, v[8:9]
	v_lshl_add_u64 v[8:9], s[6:7], 0, v[8:9]
	v_mad_u64_u32 v[10:11], s[10:11], v13, s48, v[8:9]
	v_lshlrev_b64 v[10:11], 9, v[10:11]
	s_lshl_b32 s53, s17, 10
	v_mad_u64_u32 v[8:9], s[10:11], v5, s48, v[8:9]
	v_lshl_add_u64 v[10:11], v[6:7], 0, v[10:11]
	s_add_i32 m0, s62, s53
	v_lshlrev_b64 v[8:9], 9, v[8:9]
	s_add_i32 s10, s63, 24
	global_load_lds_dwordx4 v[10:11], off
	v_lshl_add_u64 v[8:9], v[6:7], 0, v[8:9]
	s_add_i32 m0, s46, s53
	s_lshl_b32 s54, s10, 3
	global_load_lds_dwordx4 v[8:9], off
	v_add_u32_e32 v8, s54, v12
	v_max_i32_e32 v8, 0, v8
	v_mov_b32_e32 v9, v4
	v_lshlrev_b64 v[8:9], s12, v[8:9]
	v_lshl_add_u64 v[8:9], s[6:7], 0, v[8:9]
	v_mad_u64_u32 v[10:11], s[6:7], v13, s48, v[8:9]
	v_lshlrev_b64 v[10:11], 9, v[10:11]
	s_lshl_b32 s55, s10, 10
	v_mad_u64_u32 v[8:9], s[6:7], v5, s48, v[8:9]
	v_lshl_add_u64 v[10:11], v[6:7], 0, v[10:11]
	s_add_i32 m0, s62, s55
	v_lshlrev_b64 v[8:9], 9, v[8:9]
	s_lshr_b32 s6, s16, 8
	s_lshl_b32 s56, s63, 4
	v_and_b32_e32 v2, 15, v1
	global_load_lds_dwordx4 v[10:11], off
	v_lshl_add_u64 v[6:7], v[6:7], 0, v[8:9]
	s_add_i32 m0, s46, s55
	s_mul_i32 s6, s6, 0x8100
	s_add_i32 s14, s14, s56
	global_load_lds_dwordx4 v[6:7], off
	s_ashr_i32 s7, s6, 31
	v_or_b32_e32 v6, s14, v2
	v_ashrrev_i32_e32 v7, 31, v6
	s_add_u32 s4, s4, s6
	v_lshrrev_b32_e32 v3, 4, v130
	v_lshlrev_b64 v[6:7], s12, v[6:7]
	s_addc_u32 s5, s5, s7
	s_or_b32 s4, s4, s13
	v_lshlrev_b32_e32 v31, 3, v3
	v_lshl_add_u64 v[6:7], s[4:5], 0, v[6:7]
	s_and_b32 s4, s15, 0xc0
	v_lshlrev_b64 v[6:7], 9, v[6:7]
	v_or_b32_e32 v5, s4, v31
	v_lshl_add_u64 v[6:7], s[30:31], 0, v[6:7]
	v_lshlrev_b32_e32 v8, 1, v5
	v_mov_b32_e32 v9, v4
	v_lshl_add_u64 v[6:7], v[6:7], 0, v[8:9]
	global_load_dwordx4 v[18:21], v[6:7], off
	global_load_dwordx4 v[14:17], v[6:7], off offset:64
	s_movk_i32 s22, 0x81
	s_mov_b32 s41, 0
	v_and_b32_e32 v5, 7, v1
	v_cmp_gt_i32_e64 s[4:5], s22, v1
	v_mov_b32_e32 v71, 0
	s_and_saveexec_b64 s[6:7], s[4:5]
	s_cbranch_execz .LBB0_1480
	s_lshl_b32 s9, s9, 3
	s_or_b32 s8, s9, s8
	s_mulk_i32 s8, 0x84
	v_add_u32_e32 v6, s8, v1
	v_ashrrev_i32_e32 v7, 31, v6
	v_lshl_add_u64 v[6:7], v[6:7], 2, s[38:39]
	global_load_dword v71, v[6:7], off

; #define LAS __attribute__((address_space(3)))
; #define SUB(k, bit) (!(kargs()->li == 1 && (k) == lo) || ((kargs()->submask >> (bit)) & 1u))
; __global__ void __launch_bounds__(NWAVES * 64, 2) fwd(Args args_unused) {
;     ...
;             if (SUB(pb + 3, 2)) {
;                 LAS float* pbuf = (LAS float*)(lds + 98304) + wave * 136;
;                 for (int un = gw; un < 32 * 8 * 3 * 8; un += NGW) {
.LBB0_1496:
	s_cmp_lg_u32 s100, 0
	s_cbranch_scc0 .Lro_a2_0
	s_cmp_eq_u32 s98, 2
	s_cbranch_scc1 .Lro_fin_0

; #define LDS_WAIT() asm volatile("s_waitcnt lgkmcnt(0)" ::: "memory")
; #define SEAM(k) do { if (IN(k) && IN((k) + 1)) { KArgs Ab = kargs(); XcdBarrier bar_; bar_.bar = (unsigned*)(Ab->ws + WS_CTL) + CW_BAR + Ab->li * XCD_BAR_WORDS; bar_.x = xb_xcc_id(); bar_.st = MISC + 8; xcd_barrier(bar_, (int)threadIdx.x); } } while (0)
; __global__ void __launch_bounds__(NWAVES * 64, 2) fwd(Args args_unused) {
;     ...
;                     LDS_WAIT(); asm volatile("" ::: "memory");
;                 }
;                 __syncthreads();
;             }
;         }
;         SEAM(pb + 3);
.LBB0_1519:
	s_cmp_lg_u32 s100, 0
	s_cbranch_scc1 .Lro_fin_0
	s_cmp_eq_u32 s98, 0
	s_cbranch_scc1 .Lro_fin_0
	s_mov_b32 s100, 1
	s_branch .Lro_again_0

; #define LAS __attribute__((address_space(3)))
; #define SUB(k, bit) (!(kargs()->li == 1 && (k) == lo) || ((kargs()->submask >> (bit)) & 1u))
; __global__ void __launch_bounds__(NWAVES * 64, 2) fwd(Args args_unused) {
;     ...
;         if (IN(pb + 5)) {
;             PH_PTRS PH_LAYER
;             if (SUB(pb + 5, 0)) {
;                 constexpr int LT = 136, AS = 68;
;                 LAS bf16* Xs = (LAS bf16*)lds;
;                 LAS bf16* Ws = Xs + 128 * LT;
;                 LAS float* As = (LAS float*)(Ws + 128 * LT);
;                 LAS float* Us = As + 128 * AS;
;                 LAS float* sP = Us + 128 * AS;
;                 LAS float* sH = sP + 512;
;                 LAS float* cS = sH + 512;
;                 LAS float* cst = cS + 128;
;                 static_assert(2 * 128 * LT * 2 + (2 * 128 * AS + 512 + 512 + 128 + 192) * 4 <= LDSCTL_OFF, "LRU LDS map");
;                 const int qq = lane & 15, q4 = lane >> 4, w = wave;
;                 for (int un = vcu; un < 256; un += G) {
;                     const int b = un >> 4, j = (un >> 1) & 7, h2 = un & 1, chb = j * 128 + 64 * h2;
;                     __syncthreads();
;                     { const bf16* wg = (const bf16*)(wl + WL_G);
; #pragma unroll
;                       for (int k = 0; k < 4; ++k) { const int idx = tid + 512 * k, n = idx >> 4, part = idx & 15; const int srow = j * 256 + (n < 64 ? 64 * h2 + n : 128 + 64 * h2 + (n - 64));
;                           *(LAS v4u*)(Ws + n * LT + part * 8) = *(const v4u*)(wg + (size_t)srow * 128 + part * 8); }
;                       if (tid < 64) { cst[tid] = A->in[I_BR][l * DM + chb + tid]; cst[64 + tid] = A->in[I_BI][l * DM + chb + tid]; cst[128 + tid] = ((const float*)(ws + WS_SPL))[l * DM + chb + tid]; cS[tid] = 0.f; } }
;                     const int cpart = tid & 15, ctb = 4 * (tid >> 4);
;                     float cwv[4][8], cbv[8];
; #pragma unroll
;                     for (int e = 0; e < 8; ++e) { cbv[e] = A->in[I_CCB][l * DM + j * 128 + cpart * 8 + e];
; #pragma unroll
;                         for (int jj = 0; jj < 4; ++jj) cwv[jj][e] = A->in[I_CCW][(size_t)(l * 4 + jj) * DM + j * 128 + cpart * 8 + e]; }
;                     v4u xr[7] = {(v4u){0u, 0u, 0u, 0u}, (v4u){0u, 0u, 0u, 0u}, (v4u){0u, 0u, 0u, 0u}, (v4u){0u, 0u, 0u, 0u}, (v4u){0u, 0u, 0u, 0u}, (v4u){0u, 0u, 0u, 0u}, (v4u){0u, 0u, 0u, 0u}};
;     ...
;                     LRU_LOAD(0);
.LBB0_1808:
	v_readlane_b32 s99, v254, 3
	s_nop 3
	s_lshr_b32 s99, s99, 4
	s_and_b32 s98, s99, 1
	s_mov_b32 s100, 0
.Lro_again_2:
	s_cmp_lt_i32 s84, 9
	s_cselect_b64 s[4:5], -1, 0
	s_and_b64 s[0:1], s[4:5], s[0:1]
	s_andn2_b64 vcc, exec, s[0:1]
	s_cbranch_vccnz .LBB0_1930
	s_mov_b64 s[34:35], s[82:83]
	s_load_dwordx4 s[28:31], s[34:35], 0x140
	s_mov_b32 s6, 0
	s_load_dword s3, s[82:83], 0x168
	v_readlane_b32 s33, v254, 3
	s_mov_b32 s63, s2
	v_mov_b32_e32 v126, v0
	s_waitcnt lgkmcnt(0)
	s_add_u32 s26, s30, 0x1d200000
	s_addc_u32 s27, s31, 0
	v_ashrrev_i32_e32 v144, 6, v126
	s_mov_b32 s41, 0
	v_and_b32_e32 v1, 63, v126
	s_cmpk_gt_i32 s33, 0xff
	v_readfirstlane_b32 s62, v144
	s_cselect_b32 s99, 1, 0
	s_cmp_lg_u32 s100, 0
	s_cbranch_scc1 .Lro_k0_2
	s_cmp_lg_u32 s98, 0
	s_cbranch_scc1 .Lp8_post_2
.Lro_k0_2:
	s_cmp_lg_u32 s99, 0
	s_cbranch_scc1 .LBB0_1918
	v_lshlrev_b32_e32 v2, 4, v126
	v_and_b32_e32 v4, 0xf0, v2
	v_mov_b32_e32 v2, 0
	v_and_b32_e32 v3, 15, v126
	v_mov_b32_e32 v5, v2
	v_lshlrev_b32_e32 v8, 3, v126
	v_lshl_add_u64 v[6:7], s[30:31], 0, v[4:5]
	s_mov_b64 s[4:5], 0x4300000
	v_lshl_or_b32 v5, s62, 4, v3
	s_movk_i32 s47, 0x110
	s_add_i32 s7, s6, 0x22000
	s_add_i32 s40, s6, 0x22800
	s_add_i32 s64, s6, 0x23000
	s_add_i32 s44, s6, 0x23200
	v_lshl_add_u64 v[128:129], v[6:7], 0, s[4:5]
	v_add_u32_e32 v6, s6, v4
	v_lshlrev_b32_e32 v4, 2, v126
	v_and_b32_e32 v150, 56, v8
	v_mul_lo_u32 v8, v5, s47
	v_lshrrev_b32_e32 v5, 2, v126
	v_add_u32_e32 v145, s44, v4
	v_add_u32_e32 v146, s64, v4
	v_and_b32_e32 v13, 12, v5
	v_add_u32_e32 v153, s7, v4
	v_add_u32_e32 v154, s40, v4
	v_lshlrev_b32_e32 v4, 1, v150
	v_mov_b32_e32 v5, v2
	v_lshl_add_u64 v[4:5], s[30:31], 0, v[4:5]
	s_mov_b64 s[10:11], 0x79f00000
	s_add_i32 s45, s6, 0x19800
	s_add_i32 s46, s6, 0x11000
	v_lshl_add_u64 v[132:133], v[4:5], 0, s[10:11]
	v_add_u32_e32 v5, 0x200, v126
	s_add_u32 s42, s30, 0xb080000
	v_ashrrev_i32_e32 v156, 4, v5
	v_ashrrev_i32_e32 v136, 3, v5
	v_lshlrev_b32_e32 v5, 2, v13
	s_addc_u32 s43, s31, 0
	v_add_u32_e32 v151, s6, v8
	s_add_i32 s48, s6, 0x23300
	s_add_i32 s49, s6, 0x23400
	v_add3_u32 v162, s46, v8, v5
	v_add3_u32 v163, s45, v8, v5
	v_or_b32_e32 v8, 64, v5
	v_add_u32_e32 v159, s44, v5
	v_add_u32_e32 v160, s48, v5
	v_add_u32_e32 v161, s49, v5
	v_add_u32_e32 v164, s44, v8
	v_add_u32_e32 v165, s48, v8
	v_add_u32_e32 v166, s49, v8
	v_or_b32_e32 v8, 0x80, v5
	v_or_b32_e32 v5, 0xc0, v5
	v_add_u32_e32 v167, s44, v8
	v_add_u32_e32 v170, s44, v5
	s_movk_i32 s44, 0x440
	v_add_u32_e32 v171, s48, v5
	v_add_u32_e32 v172, s49, v5
	v_mul_lo_u32 v5, v144, s44
	v_or_b32_e32 v5, v5, v1
	v_lshlrev_b32_e32 v5, 2, v5
	v_add_u32_e32 v173, s46, v5
	v_add_u32_e32 v174, s45, v5
	v_lshl_or_b32 v5, v144, 4, 1
	s_movk_i32 s44, 0x44
	v_add_u32_e32 v168, s48, v8
	v_add_u32_e32 v169, s49, v8
	v_mul_lo_u32 v8, v5, s44
	v_lshlrev_b32_e32 v10, 2, v1
	v_add_u32_e32 v19, v8, v1
	v_add_u32_e32 v14, s45, v10
	v_lshl_add_u32 v175, v19, 2, s46
	v_add_u32_e32 v19, 0x44, v8
	v_add_u32_e32 v20, v19, v1
	v_lshl_add_u32 v178, v19, 2, v14
	v_add_u32_e32 v19, 0x88, v8
	v_lshl_add_u32 v177, v20, 2, s46
	v_add_u32_e32 v20, v19, v1
	v_lshl_add_u32 v180, v19, 2, v14
	v_add_u32_e32 v19, 0xcc, v8
	v_lshl_add_u32 v179, v20, 2, s46
	v_add_u32_e32 v20, v19, v1
	v_lshl_add_u32 v182, v19, 2, v14
	v_add_u32_e32 v19, 0x110, v8
	v_lshl_add_u32 v181, v20, 2, s46
	v_add_u32_e32 v20, v19, v1
	v_lshl_add_u32 v184, v19, 2, v14
	v_add_u32_e32 v19, 0x154, v8
	v_lshl_add_u32 v183, v20, 2, s46
	v_add_u32_e32 v20, v19, v1
	v_lshl_add_u32 v186, v19, 2, v14
	v_add_u32_e32 v19, 0x198, v8
	v_lshl_add_u32 v185, v20, 2, s46
	v_add_u32_e32 v20, v19, v1
	v_lshl_add_u32 v188, v19, 2, v14
	v_add_u32_e32 v19, 0x1dc, v8
	v_lshl_add_u32 v187, v20, 2, s46
	v_add_u32_e32 v20, v19, v1
	v_lshl_add_u32 v190, v19, 2, v14
	v_add_u32_e32 v19, 0x220, v8
	v_lshl_add_u32 v189, v20, 2, s46
	v_add_u32_e32 v20, v19, v1
	v_lshl_add_u32 v192, v19, 2, v14
	v_add_u32_e32 v19, 0x264, v8
	v_lshl_add_u32 v191, v20, 2, s46
	v_add_u32_e32 v20, v19, v1
	v_lshl_add_u32 v194, v19, 2, v14
	v_add_u32_e32 v19, 0x2a8, v8
	v_lshl_add_u32 v193, v20, 2, s46
	v_add_u32_e32 v20, v19, v1
	v_lshl_add_u32 v196, v19, 2, v14
	v_add_u32_e32 v19, 0x2ec, v8
	s_load_dwordx4 s[36:39], s[34:35], 0xd8
	v_lshl_add_u32 v195, v20, 2, s46
	v_add_u32_e32 v20, v19, v1
	v_lshl_add_u32 v198, v19, 2, v14
	v_add_u32_e32 v19, 0x330, v8
	v_ashrrev_i32_e32 v7, 2, v126
	v_add_u32_e32 v17, 0x400, v126
	v_add_u32_e32 v18, 0x600, v126
	v_lshl_add_u32 v176, v8, 2, v14
	v_lshl_add_u32 v197, v20, 2, s46
	v_add_u32_e32 v20, v19, v1
	v_lshl_add_u32 v200, v19, 2, v14
	v_add_u32_e32 v19, 0x374, v8
	v_add_u32_e32 v8, 0x3b8, v8
	v_and_b32_e32 v9, -4, v7
	v_and_b32_e32 v152, 48, v126
	v_ashrrev_i32_e32 v155, 4, v126
	v_ashrrev_i32_e32 v157, 4, v17
	v_ashrrev_i32_e32 v158, 4, v18
	v_cmp_lt_i32_e64 s[18:19], 3, v7
	v_cmp_lt_i32_e64 s[20:21], -1, v7
	v_or_b32_e32 v7, 3, v7
	v_ashrrev_i32_e32 v134, 3, v126
	v_lshl_add_u32 v199, v20, 2, s46
	v_add_u32_e32 v20, v19, v1
	v_lshl_add_u32 v202, v19, 2, v14
	v_add_u32_e32 v19, v8, v1
	s_movk_i32 s44, 0x1100
	v_lshlrev_b32_e32 v147, 3, v3
	v_add_u32_e32 v130, -3, v9
	v_lshl_add_u32 v11, v3, 4, s6
	v_add_u32_e32 v149, 0x7d, v9
	v_add_u32_e32 v12, s6, v152
	v_lshl_add_u32 v15, v150, 2, s45
	v_mul_lo_u32 v4, v155, s47
	v_mul_lo_u32 v16, v156, s47
	v_mul_lo_u32 v17, v157, s47
	v_mul_lo_u32 v18, v158, s47
	v_cmp_lt_i32_e64 s[22:23], -2, v9
	v_cmp_lt_i32_e64 s[24:25], -3, v9
	v_mul_lo_u32 v9, v9, s47
	v_mul_lo_u32 v7, v7, s47
	v_mul_u32_u24_e32 v3, 0x110, v3
	v_lshl_add_u32 v201, v20, 2, s46
	v_lshl_add_u32 v203, v19, 2, s46
	v_lshl_add_u32 v204, v8, 2, v14
	v_mul_lo_u32 v8, v144, s44
	v_mul_lo_u32 v5, v5, s47
	v_mul_lo_u32 v19, v134, s47
	v_mul_lo_u32 v20, v136, s47
	v_cmp_gt_i32_e64 s[4:5], 64, v126
	v_ashrrev_i32_e32 v131, 31, v130
	v_add_u32_e32 v148, s64, v10
	v_cmp_lt_i32_e64 s[6:7], 0, v144
	v_cmp_eq_u32_e64 s[8:9], 7, v144
	v_ashrrev_i32_e32 v127, 31, v126
	v_cmp_gt_i32_e64 s[10:11], 64, v155
	v_cmp_gt_i32_e64 s[12:13], 64, v156
	v_cmp_gt_i32_e64 s[14:15], 64, v157
	v_cmp_gt_i32_e64 s[16:17], 64, v158
	v_ashrrev_i32_e32 v135, 31, v134
	v_ashrrev_i32_e32 v137, 31, v136
	v_lshl_add_u32 v205, v13, 1, v151
	v_add_u32_e32 v206, s40, v10
	v_add_u32_e32 v207, v6, v4
	v_add_u32_e32 v208, v6, v16
	v_add_u32_e32 v209, v6, v17
	v_add_u32_e32 v210, v6, v18
	s_mov_b64 s[44:45], 0x1000
	s_mov_b64 s[46:47], 0x2000
	s_mov_b64 s[48:49], 0x3000
	v_add_u32_e32 v211, v11, v9
	v_add_u32_e32 v212, v11, v7
	v_add_u32_e32 v213, v12, v3
	s_mov_b32 s65, 0xbecccccd
	v_mov_b32_e32 v214, 0x3c088889
	v_add_u32_e32 v215, v14, v8
	v_add_u32_e32 v216, v14, v5
	v_add_u32_e32 v217, v15, v19
	v_add_u32_e32 v218, v15, v20
	s_mov_b32 s66, s33
	s_branch .LBB0_1812

; #define SUB(k, bit) (!(kargs()->li == 1 && (k) == lo) || ((kargs()->submask >> (bit)) & 1u))
; __global__ void __launch_bounds__(NWAVES * 64, 2) fwd(Args args_unused) {
;     ...
;             if (SUB(pb + 5, 1))
;             for (int row0 = gw; row0 < M; row0 += 2 * NGW) {
;                 const int hh = lane >> 3;
;                 float l0[2], l1[2], l2[2]; v4u r0[2], r1[2], r2[2], yr[2][2], zr[2][2];
; #pragma unroll
;                 for (int k = 0; k < 2; ++k) { const int row = row0 + k * NGW;
;                     l0[k] = 0.f; l1[k] = 0.f; l2[k] = 0.f; r0[k] = (v4u){0u, 0u, 0u, 0u}; r1[k] = (v4u){0u, 0u, 0u, 0u}; r2[k] = (v4u){0u, 0u, 0u, 0u};
; #pragma unroll
;                     for (int q = 0; q < 2; ++q) { yr[k][q] = (v4u){0u, 0u, 0u, 0u}; zr[k][q] = (v4u){0u, 0u, 0u, 0u}; }
;                     if (row < M) {
;                         l0[k] = LSE[((size_t)0 * M + row) * 8 + hh]; l1[k] = LSE[((size_t)1 * M + row) * 8 + hh]; l2[k] = LSE[((size_t)2 * M + row) * 8 + hh];
;                         r0[k] = *(const v4u*)(OG + ((size_t)0 * M + row) * 512 + 8 * lane); r1[k] = *(const v4u*)(OG + ((size_t)1 * M + row) * 512 + 8 * lane); r2[k] = *(const v4u*)(OG + ((size_t)2 * M + row) * 512 + 8 * lane);
; #pragma unroll
;                         for (int q = 0; q < 2; ++q) { const int col = q * 512 + 8 * lane; yr[k][q] = *(const v4u*)(YS + (size_t)row * DM + col); zr[k][q] = *(const v4u*)ZP(Z, row, ZZB + col); } } }
.Lro_p8_2:
	s_lshl_b32 s4, s33, 3
	s_add_i32 s4, s4, s62
	s_cmp_lt_i32 s4, 0x8100
	s_mov_b32 s5, 0x8100
	s_cbranch_scc0 .LBB0_1930
	s_load_dwordx2 s[6:7], s[34:35], 0xc8
	v_lshlrev_b32_e32 v18, 5, v1
	v_mov_b32_e32 v75, 0
	v_mov_b32_e32 v20, 0x91200
	s_lshl_b32 s12, s3, 3
	s_waitcnt lgkmcnt(0)
	global_load_dwordx4 v[2:5], v18, s[6:7]
	global_load_dwordx4 v[6:9], v18, s[6:7] offset:16
	global_load_dwordx4 v[10:13], v18, s[6:7] offset:2048
	global_load_dwordx4 v[14:17], v18, s[6:7] offset:2064
	v_lshrrev_b32_e32 v18, 1, v1
	v_and_b32_e32 v74, 28, v18
	v_lshl_add_u64 v[18:19], s[30:31], 0, v[74:75]
	s_mov_b64 s[6:7], 0xb800000
	v_lshlrev_b32_e32 v74, 4, v1
	v_lshl_add_u64 v[76:77], v[18:19], 0, s[6:7]
	v_lshl_add_u64 v[18:19], s[30:31], 0, v[74:75]
	s_mov_b64 s[6:7], 0x67c00000
	v_lshl_add_u64 v[78:79], v[18:19], 0, s[6:7]
	v_and_b32_e32 v74, 0x1f0, v74
	s_mov_b64 s[6:7], 0x75e00000
	v_lshrrev_b32_e32 v1, 5, v1
	v_lshl_add_u64 v[80:81], s[26:27], 0, v[74:75]
	v_lshl_add_u64 v[82:83], v[18:19], 0, s[6:7]
	v_mad_u32_u24 v74, v1, s5, v20
	v_mov_b32_e32 v20, 0xa1400
	s_mov_b64 s[6:7], 0x6dd00000
	v_mad_u32_u24 v84, v1, s5, v20
	v_lshl_add_u64 v[86:87], v[18:19], 0, s[6:7]
	s_mov_b64 s[6:7], 0x5fb00000
	v_mbcnt_lo_u32_b32 v1, -1, 0
	v_mov_b32_e32 v85, v75
	v_lshl_add_u64 v[88:89], v[18:19], 0, s[6:7]
	s_lshl_b32 s3, s3, 4
	v_mbcnt_hi_u32_b32 v1, -1, v1
	v_mov_b32_e32 v90, 0x358637bd
	s_branch .LBB0_1926

; #define SUB(k, bit) (!(kargs()->li == 1 && (k) == lo) || ((kargs()->submask >> (bit)) & 1u))
; __global__ void __launch_bounds__(NWAVES * 64, 2) fwd(Args args_unused) {
;     ...
;         if (IN(pb + 3)) {
;             PH_PTRS PH_LAYER
;             if (SUB(pb + 3, 0)) {
;                 const int nitems = (M / 16) * 5;
; #pragma unroll 1
;                 for (int it = gw; it < nitems; it += NGW) {
;                     const int seg = it / 5, c = (it - seg * 5) * 64 + lane;
;                     if (c >= 192 && seg * 16 < NPROMPT) continue;
.Lro_again_1:
	s_cmp_lt_i32 s84, 17
	s_cselect_b64 s[0:1], -1, 0
	s_cmp_gt_i32 s85, 16
	s_waitcnt lgkmcnt(0)
	s_cselect_b64 s[4:5], -1, 0
	s_and_b64 s[0:1], s[0:1], s[4:5]
	s_andn2_b64 vcc, exec, s[0:1]
	s_cbranch_vccnz .LBB0_3545
	s_mov_b64 s[26:27], s[82:83]
	s_load_dwordx2 s[28:29], s[26:27], 0x148
	s_mov_b32 s62, 0
	s_mov_b32 s3, s2
	s_load_dword s64, s[82:83], 0x168
	v_readlane_b32 s33, v254, 3
	v_mov_b32_e32 v1, v0
	s_waitcnt lgkmcnt(0)
	s_lshl_b32 s4, s33, 3
	v_readfirstlane_b32 s61, v1
	s_ashr_i32 s63, s61, 6
	s_lshl_b32 s3, s64, 3
	s_add_i32 s60, s63, s4
	s_add_u32 s30, s28, 0x1d200000
	s_addc_u32 s31, s29, 0
	s_cmpk_gt_i32 s60, 0x284f
	v_and_b32_e32 v130, 63, v1
	s_cselect_b32 s99, 1, 0
	s_cmp_lg_u32 s100, 0
	s_cbranch_scc1 .Lro_k0_1
	s_cmp_lg_u32 s98, 0
	s_cbranch_scc1 .LBB0_3502
.Lro_k0_1:
	s_cmp_lg_u32 s99, 0
	s_cbranch_scc1 .LBB0_3502
	s_add_u32 s8, s28, 0x4d800000
	s_addc_u32 s9, s29, 0
	s_add_u32 s10, s28, 0x53900000
	s_addc_u32 s11, s29, 0
	s_lshl_b32 s4, s33, 9
	s_lshl_b32 s5, s63, 6
	s_add_i32 s4, s4, s5
	v_or_b32_e32 v131, s4, v130
	v_lshlrev_b32_e32 v140, 3, v131
	s_lshl_b32 s65, s64, 12
	s_lshl_b32 s66, s64, 9
	s_movk_i32 s67, 0xc0
	s_movk_i32 s68, 0xbf
	v_mov_b32_e32 v133, 0
	v_mov_b32_e32 v141, 0x400
	v_mov_b32_e32 v142, 0x600
	v_mov_b32_e32 v143, 0x1c00
	v_mov_b32_e32 v144, 0x1600
	v_mov_b32_e32 v145, 0xd8
	v_mov_b32_e32 v146, 0xa0
	v_mov_b32_e32 v147, 0x4000
	v_mov_b32_e32 v148, 0x6000
	v_mov_b32_e32 v149, 0xe0
	v_mov_b32_e32 v150, 0xa8
	v_mov_b32_e32 v151, 0x1000
	v_mov_b32_e32 v152, 0x1800
	v_mov_b32_e32 v153, 0xc00
	s_mov_b32 s69, s60
	s_branch .LBB0_3393

; #define LAS __attribute__((address_space(3)))
; __global__ void __launch_bounds__(NWAVES * 64, 2) fwd(Args args_unused) {
;     ...
;                 LAS unsigned char* KB0 = lds; LAS unsigned char* VB0 = lds + 65536; LAS float* bsm = (LAS float*)(lds + 131072);
;                 const int qq = lane & 15, q4 = lane >> 4, w = wave;
;                 constexpr int NUN = 16 * 3 * 8 * 16;
;     ...
;                 bf16x8 qn[2] = {(bf16x8){0, 0, 0, 0, 0, 0, 0, 0}, (bf16x8){0, 0, 0, 0, 0, 0, 0, 0}}; float bnx = 0.f;
;                 __syncthreads();
;                 if (vcu < NUN) ATT_ISSUE(vcu, 0, qn);
.Lro_a1_1:
	s_add_u32 s34, s28, 0xb800000
	s_addc_u32 s35, s29, 0
	s_add_u32 s36, s28, 0x67c00000
	s_addc_u32 s37, s29, 0
	s_cmpk_gt_i32 s33, 0x17ff
	s_waitcnt vmcnt(0)
	s_barrier
	s_cselect_b32 s99, 1, 0
	s_cmp_lg_u32 s100, 0
	s_cbranch_scc1 .Lro_k2_1
	s_cmp_eq_u32 s98, 2
	s_cbranch_scc1 .LBB0_3521
.Lro_k2_1:
	s_cmp_lg_u32 s99, 0
	s_cbranch_scc1 .LBB0_3521
	s_add_i32 s46, s62, 0x10000
	s_add_u32 s38, s28, 0xb000000
	s_addc_u32 s39, s29, 0
	s_ashr_i32 s4, s33, 7
	s_mul_hi_i32 s6, s4, 0x55555556
	s_lshr_b32 s7, s6, 31
	s_add_i32 s6, s6, s7
	s_mul_i32 s6, s6, 3
	s_sub_i32 s9, s4, s6
	s_mul_hi_i32 s4, s33, 0x2aaaaaab
	s_lshr_b32 s6, s4, 31
	s_ashr_i32 s4, s4, 6
	s_and_b32 s5, s33, 15
	s_bfe_u32 s8, s33, 0x30004
	s_add_i32 s4, s4, s6
	s_cmp_eq_u32 s9, 1
	s_cselect_b32 s6, 2, 4
	s_cmp_lg_u32 s9, 0
	s_cselect_b32 s12, s6, 0
	s_sub_i32 s7, 4, s12
	v_lshrrev_b32_e32 v4, 3, v130
	s_lshr_b32 s6, 16, s12
	s_lshr_b32 s13, s5, s7
	v_bitop3_b32 v5, v4, v1, 7 bitop3:0x78
	s_lshl_b32 s10, s9, 9
	s_lshl_b32 s15, s8, 6
	s_mul_i32 s6, s13, s6
	s_or_b32 s16, s10, s15
	v_lshlrev_b32_e32 v29, 3, v5
	s_sub_i32 s5, s5, s6
	v_or_b32_e32 v5, s16, v29
	s_lshl_b32 s14, s5, 7
	v_or_b32_e32 v28, 0xffffff80, v4
	v_add_u32_e32 v4, 0x600, v5
	v_mov_b32_e32 v30, 0xf8
	v_add_u32_e32 v12, s14, v28
	v_lshrrev_b32_e32 v13, 8, v4
	v_bitop3_b32 v4, s16, v30, v29 bitop3:0xc8
	s_lshl_b32 s47, s63, 3
	s_ashr_i32 s5, s4, 31
	v_lshlrev_b32_e32 v6, 1, v4
	v_mov_b32_e32 v4, 0
	v_add_u32_e32 v8, s47, v12
	s_lshl_b64 s[4:5], s[4:5], 11
	v_max_i32_e32 v8, 0, v8
	v_mov_b32_e32 v9, v4
	s_or_b32 s6, s4, s13
	s_mov_b32 s7, s5
	v_lshlrev_b64 v[8:9], s12, v[8:9]
	v_add_u32_e32 v5, 0xc00, v5
	v_lshl_add_u64 v[8:9], s[6:7], 0, v[8:9]
	s_mov_b32 s48, 0x8100
	v_mov_b32_e32 v7, v4
	v_lshrrev_b32_e32 v5, 8, v5
	v_mad_u64_u32 v[10:11], s[10:11], v13, s48, v[8:9]
	v_lshl_add_u64 v[6:7], s[30:31], 0, v[6:7]
	v_lshlrev_b64 v[10:11], 9, v[10:11]
	s_lshl_b32 s49, s63, 10
	v_mad_u64_u32 v[8:9], s[10:11], v5, s48, v[8:9]
	v_lshl_add_u64 v[10:11], v[6:7], 0, v[10:11]
	s_add_i32 m0, s62, s49
	v_lshlrev_b64 v[8:9], 9, v[8:9]
	s_add_i32 s24, s63, 8
	global_load_lds_dwordx4 v[10:11], off
	v_lshl_add_u64 v[8:9], v[6:7], 0, v[8:9]
	s_add_i32 m0, s46, s49
	s_lshl_b32 s50, s24, 3
	global_load_lds_dwordx4 v[8:9], off
	v_add_u32_e32 v8, s50, v12
	v_max_i32_e32 v8, 0, v8
	v_mov_b32_e32 v9, v4
	v_lshlrev_b64 v[8:9], s12, v[8:9]
	v_lshl_add_u64 v[8:9], s[6:7], 0, v[8:9]
	v_mad_u64_u32 v[10:11], s[10:11], v13, s48, v[8:9]
	v_lshlrev_b64 v[10:11], 9, v[10:11]
	s_lshl_b32 s51, s24, 10
	v_mad_u64_u32 v[8:9], s[10:11], v5, s48, v[8:9]
	v_lshl_add_u64 v[10:11], v[6:7], 0, v[10:11]
	s_add_i32 m0, s62, s51
	v_lshlrev_b64 v[8:9], 9, v[8:9]
	s_add_i32 s17, s63, 16
	global_load_lds_dwordx4 v[10:11], off
	v_lshl_add_u64 v[8:9], v[6:7], 0, v[8:9]
	s_add_i32 m0, s46, s51
	s_lshl_b32 s52, s17, 3
	global_load_lds_dwordx4 v[8:9], off
	v_add_u32_e32 v8, s52, v12
	v_max_i32_e32 v8, 0, v8
	v_mov_b32_e32 v9, v4
	v_lshlrev_b64 v[8:9], s12, v[8:9]
	v_lshl_add_u64 v[8:9], s[6:7], 0, v[8:9]
	v_mad_u64_u32 v[10:11], s[10:11], v13, s48, v[8:9]
	v_lshlrev_b64 v[10:11], 9, v[10:11]
	s_lshl_b32 s53, s17, 10
	v_mad_u64_u32 v[8:9], s[10:11], v5, s48, v[8:9]
	v_lshl_add_u64 v[10:11], v[6:7], 0, v[10:11]
	s_add_i32 m0, s62, s53
	v_lshlrev_b64 v[8:9], 9, v[8:9]
	s_add_i32 s10, s63, 24
	global_load_lds_dwordx4 v[10:11], off
	v_lshl_add_u64 v[8:9], v[6:7], 0, v[8:9]
	s_add_i32 m0, s46, s53
	s_lshl_b32 s54, s10, 3
	global_load_lds_dwordx4 v[8:9], off
	v_add_u32_e32 v8, s54, v12
	v_max_i32_e32 v8, 0, v8
	v_mov_b32_e32 v9, v4
	v_lshlrev_b64 v[8:9], s12, v[8:9]
	v_lshl_add_u64 v[8:9], s[6:7], 0, v[8:9]
	v_mad_u64_u32 v[10:11], s[6:7], v13, s48, v[8:9]
	v_lshlrev_b64 v[10:11], 9, v[10:11]
	s_lshl_b32 s55, s10, 10
	v_mad_u64_u32 v[8:9], s[6:7], v5, s48, v[8:9]
	v_lshl_add_u64 v[10:11], v[6:7], 0, v[10:11]
	s_add_i32 m0, s62, s55
	v_lshlrev_b64 v[8:9], 9, v[8:9]
	s_lshr_b32 s6, s16, 8
	s_lshl_b32 s56, s63, 4
	v_and_b32_e32 v2, 15, v1
	global_load_lds_dwordx4 v[10:11], off
	v_lshl_add_u64 v[6:7], v[6:7], 0, v[8:9]
	s_add_i32 m0, s46, s55
	s_mul_i32 s6, s6, 0x8100
	s_add_i32 s14, s14, s56
	global_load_lds_dwordx4 v[6:7], off
	s_ashr_i32 s7, s6, 31
	v_or_b32_e32 v6, s14, v2
	v_ashrrev_i32_e32 v7, 31, v6
	s_add_u32 s4, s4, s6
	v_lshrrev_b32_e32 v3, 4, v130
	v_lshlrev_b64 v[6:7], s12, v[6:7]
	s_addc_u32 s5, s5, s7
	s_or_b32 s4, s4, s13
	v_lshlrev_b32_e32 v31, 3, v3
	v_lshl_add_u64 v[6:7], s[4:5], 0, v[6:7]
	s_and_b32 s4, s15, 0xc0
	v_lshlrev_b64 v[6:7], 9, v[6:7]
	v_or_b32_e32 v5, s4, v31
	v_lshl_add_u64 v[6:7], s[30:31], 0, v[6:7]
	v_lshlrev_b32_e32 v8, 1, v5
	v_mov_b32_e32 v9, v4
	v_lshl_add_u64 v[6:7], v[6:7], 0, v[8:9]
	global_load_dwordx4 v[18:21], v[6:7], off
	global_load_dwordx4 v[14:17], v[6:7], off offset:64
	s_movk_i32 s22, 0x81
	s_mov_b32 s41, 0
	v_and_b32_e32 v5, 7, v1
	v_cmp_gt_i32_e64 s[4:5], s22, v1
	v_mov_b32_e32 v71, 0
	s_and_saveexec_b64 s[6:7], s[4:5]
	s_cbranch_execz .LBB0_3505
	s_lshl_b32 s9, s9, 3
	s_or_b32 s8, s9, s8
	s_mulk_i32 s8, 0x84
	v_add_u32_e32 v6, s8, v1
	v_ashrrev_i32_e32 v7, 31, v6
	v_lshl_add_u64 v[6:7], v[6:7], 2, s[38:39]
	global_load_dword v71, v[6:7], off

; #define LAS __attribute__((address_space(3)))
; #define SUB(k, bit) (!(kargs()->li == 1 && (k) == lo) || ((kargs()->submask >> (bit)) & 1u))
; __global__ void __launch_bounds__(NWAVES * 64, 2) fwd(Args args_unused) {
;     ...
;         if (IN(pb + 5)) {
;             PH_PTRS PH_LAYER
;             if (SUB(pb + 5, 0)) {
;                 constexpr int LT = 136, AS = 68;
;                 LAS bf16* Xs = (LAS bf16*)lds;
;                 LAS bf16* Ws = Xs + 128 * LT;
;                 LAS float* As = (LAS float*)(Ws + 128 * LT);
;                 LAS float* Us = As + 128 * AS;
;                 LAS float* sP = Us + 128 * AS;
;                 LAS float* sH = sP + 512;
;                 LAS float* cS = sH + 512;
;                 LAS float* cst = cS + 128;
;                 static_assert(2 * 128 * LT * 2 + (2 * 128 * AS + 512 + 512 + 128 + 192) * 4 <= LDSCTL_OFF, "LRU LDS map");
;                 const int qq = lane & 15, q4 = lane >> 4, w = wave;
;                 for (int un = vcu; un < 256; un += G) {
;                     const int b = un >> 4, j = (un >> 1) & 7, h2 = un & 1, chb = j * 128 + 64 * h2;
;                     __syncthreads();
;                     { const bf16* wg = (const bf16*)(wl + WL_G);
; #pragma unroll
;                       for (int k = 0; k < 4; ++k) { const int idx = tid + 512 * k, n = idx >> 4, part = idx & 15; const int srow = j * 256 + (n < 64 ? 64 * h2 + n : 128 + 64 * h2 + (n - 64));
;                           *(LAS v4u*)(Ws + n * LT + part * 8) = *(const v4u*)(wg + (size_t)srow * 128 + part * 8); }
;                       if (tid < 64) { cst[tid] = A->in[I_BR][l * DM + chb + tid]; cst[64 + tid] = A->in[I_BI][l * DM + chb + tid]; cst[128 + tid] = ((const float*)(ws + WS_SPL))[l * DM + chb + tid]; cS[tid] = 0.f; } }
;                     const int cpart = tid & 15, ctb = 4 * (tid >> 4);
;                     float cwv[4][8], cbv[8];
; #pragma unroll
;                     for (int e = 0; e < 8; ++e) { cbv[e] = A->in[I_CCB][l * DM + j * 128 + cpart * 8 + e];
; #pragma unroll
;                         for (int jj = 0; jj < 4; ++jj) cwv[jj][e] = A->in[I_CCW][(size_t)(l * 4 + jj) * DM + j * 128 + cpart * 8 + e]; }
;                     v4u xr[7] = {(v4u){0u, 0u, 0u, 0u}, (v4u){0u, 0u, 0u, 0u}, (v4u){0u, 0u, 0u, 0u}, (v4u){0u, 0u, 0u, 0u}, (v4u){0u, 0u, 0u, 0u}, (v4u){0u, 0u, 0u, 0u}, (v4u){0u, 0u, 0u, 0u}};
;     ...
;                     LRU_LOAD(0);
.Lro_again_3:
	s_cmp_lt_i32 s84, 19
	s_cselect_b64 s[4:5], -1, 0
	s_and_b64 s[0:1], s[4:5], s[0:1]
	s_andn2_b64 vcc, exec, s[0:1]
	s_cbranch_vccnz .LBB0_3954
	s_mov_b64 s[34:35], s[82:83]
	s_load_dwordx4 s[28:31], s[34:35], 0x140
	s_mov_b32 s6, 0
	s_mov_b32 s63, s2
	s_load_dword s3, s[82:83], 0x168
	v_readlane_b32 s33, v254, 3
	v_mov_b32_e32 v126, v0
	s_waitcnt lgkmcnt(0)
	s_add_u32 s26, s30, 0x1d200000
	s_addc_u32 s27, s31, 0
	v_ashrrev_i32_e32 v144, 6, v126
	s_mov_b32 s41, 0
	v_and_b32_e32 v1, 63, v126
	s_cmpk_gt_i32 s33, 0xff
	v_readfirstlane_b32 s62, v144
	s_cselect_b32 s99, 1, 0
	s_cmp_lg_u32 s100, 0
	s_cbranch_scc1 .Lro_k0_3
	s_cmp_lg_u32 s98, 0
	s_cbranch_scc1 .Lp8_post_3
.Lro_k0_3:
	s_cmp_lg_u32 s99, 0
	s_cbranch_scc1 .LBB0_3942
	v_lshlrev_b32_e32 v2, 4, v126
	v_and_b32_e32 v4, 0xf0, v2
	v_mov_b32_e32 v2, 0
	v_and_b32_e32 v3, 15, v126
	v_mov_b32_e32 v5, v2
	v_lshlrev_b32_e32 v8, 3, v126
	v_lshl_add_u64 v[6:7], s[30:31], 0, v[4:5]
	s_mov_b64 s[4:5], 0x8800000
	v_lshl_or_b32 v5, s62, 4, v3
	s_movk_i32 s47, 0x110
	s_add_i32 s7, s6, 0x22000
	s_add_i32 s40, s6, 0x22800
	s_add_i32 s64, s6, 0x23000
	s_add_i32 s44, s6, 0x23200
	v_lshl_add_u64 v[128:129], v[6:7], 0, s[4:5]
	v_add_u32_e32 v6, s6, v4
	v_lshlrev_b32_e32 v4, 2, v126
	v_and_b32_e32 v153, 56, v8
	v_mul_lo_u32 v8, v5, s47
	v_lshrrev_b32_e32 v5, 2, v126
	v_add_u32_e32 v146, s44, v4
	v_add_u32_e32 v147, s64, v4
	v_and_b32_e32 v13, 12, v5
	v_add_u32_e32 v156, s7, v4
	v_add_u32_e32 v157, s40, v4
	v_lshlrev_b32_e32 v4, 1, v153
	v_mov_b32_e32 v5, v2
	v_lshl_add_u64 v[4:5], s[30:31], 0, v[4:5]
	s_mov_b64 s[10:11], 0x79f00000
	s_add_i32 s45, s6, 0x19800
	s_add_i32 s46, s6, 0x11000
	v_lshl_add_u64 v[132:133], v[4:5], 0, s[10:11]
	v_add_u32_e32 v5, 0x200, v126
	s_add_u32 s42, s30, 0xb080000
	v_ashrrev_i32_e32 v159, 4, v5
	v_ashrrev_i32_e32 v136, 3, v5
	v_lshlrev_b32_e32 v5, 2, v13
	s_addc_u32 s43, s31, 0
	v_add_u32_e32 v154, s6, v8
	s_add_i32 s48, s6, 0x23300
	s_add_i32 s49, s6, 0x23400
	v_add3_u32 v165, s46, v8, v5
	v_add3_u32 v166, s45, v8, v5
	v_or_b32_e32 v8, 64, v5
	v_add_u32_e32 v162, s44, v5
	v_add_u32_e32 v163, s48, v5
	v_add_u32_e32 v164, s49, v5
	v_add_u32_e32 v167, s44, v8
	v_add_u32_e32 v168, s48, v8
	v_add_u32_e32 v169, s49, v8
	v_or_b32_e32 v8, 0x80, v5
	v_or_b32_e32 v5, 0xc0, v5
	v_add_u32_e32 v170, s44, v8
	v_add_u32_e32 v173, s44, v5
	s_movk_i32 s44, 0x440
	v_add_u32_e32 v174, s48, v5
	v_add_u32_e32 v175, s49, v5
	v_mul_lo_u32 v5, v144, s44
	v_or_b32_e32 v5, v5, v1
	v_lshlrev_b32_e32 v5, 2, v5
	v_add_u32_e32 v176, s46, v5
	v_add_u32_e32 v177, s45, v5
	v_lshl_or_b32 v5, v144, 4, 1
	s_movk_i32 s44, 0x44
	v_add_u32_e32 v171, s48, v8
	v_add_u32_e32 v172, s49, v8
	v_mul_lo_u32 v8, v5, s44
	v_lshlrev_b32_e32 v10, 2, v1
	v_add_u32_e32 v19, v8, v1
	v_add_u32_e32 v14, s45, v10
	v_lshl_add_u32 v178, v19, 2, s46
	v_add_u32_e32 v19, 0x44, v8
	v_add_u32_e32 v20, v19, v1
	v_lshl_add_u32 v181, v19, 2, v14
	v_add_u32_e32 v19, 0x88, v8
	v_lshl_add_u32 v180, v20, 2, s46
	v_add_u32_e32 v20, v19, v1
	v_lshl_add_u32 v183, v19, 2, v14
	v_add_u32_e32 v19, 0xcc, v8
	v_lshl_add_u32 v182, v20, 2, s46
	v_add_u32_e32 v20, v19, v1
	v_lshl_add_u32 v185, v19, 2, v14
	v_add_u32_e32 v19, 0x110, v8
	v_lshl_add_u32 v184, v20, 2, s46
	v_add_u32_e32 v20, v19, v1
	v_lshl_add_u32 v187, v19, 2, v14
	v_add_u32_e32 v19, 0x154, v8
	v_lshl_add_u32 v186, v20, 2, s46
	v_add_u32_e32 v20, v19, v1
	v_lshl_add_u32 v189, v19, 2, v14
	v_add_u32_e32 v19, 0x198, v8
	v_lshl_add_u32 v188, v20, 2, s46
	v_add_u32_e32 v20, v19, v1
	v_lshl_add_u32 v191, v19, 2, v14
	v_add_u32_e32 v19, 0x1dc, v8
	v_lshl_add_u32 v190, v20, 2, s46
	v_add_u32_e32 v20, v19, v1
	v_lshl_add_u32 v193, v19, 2, v14
	v_add_u32_e32 v19, 0x220, v8
	v_lshl_add_u32 v192, v20, 2, s46
	v_add_u32_e32 v20, v19, v1
	v_lshl_add_u32 v195, v19, 2, v14
	v_add_u32_e32 v19, 0x264, v8
	v_lshl_add_u32 v194, v20, 2, s46
	v_add_u32_e32 v20, v19, v1
	v_lshl_add_u32 v197, v19, 2, v14
	v_add_u32_e32 v19, 0x2a8, v8
	v_lshl_add_u32 v196, v20, 2, s46
	v_add_u32_e32 v20, v19, v1
	v_lshl_add_u32 v199, v19, 2, v14
	v_add_u32_e32 v19, 0x2ec, v8
	s_load_dwordx4 s[36:39], s[34:35], 0xd8
	v_lshl_add_u32 v198, v20, 2, s46
	v_add_u32_e32 v20, v19, v1
	v_lshl_add_u32 v201, v19, 2, v14
	v_add_u32_e32 v19, 0x330, v8
	v_add_u32_e32 v145, 0x400, v126
	v_ashrrev_i32_e32 v7, 2, v126
	v_add_u32_e32 v18, 0x600, v126
	v_lshl_add_u32 v179, v8, 2, v14
	v_lshl_add_u32 v200, v20, 2, s46
	v_add_u32_e32 v20, v19, v1
	v_lshl_add_u32 v203, v19, 2, v14
	v_add_u32_e32 v19, 0x374, v8
	v_add_u32_e32 v8, 0x3b8, v8
	v_and_b32_e32 v9, -4, v7
	v_and_b32_e32 v155, 48, v126
	v_ashrrev_i32_e32 v158, 4, v126
	v_ashrrev_i32_e32 v160, 4, v145
	v_ashrrev_i32_e32 v161, 4, v18
	v_cmp_lt_i32_e64 s[18:19], 3, v7
	v_cmp_lt_i32_e64 s[20:21], -1, v7
	v_or_b32_e32 v7, 3, v7
	v_ashrrev_i32_e32 v134, 3, v126
	v_lshl_add_u32 v202, v20, 2, s46
	v_add_u32_e32 v20, v19, v1
	v_lshl_add_u32 v205, v19, 2, v14
	v_add_u32_e32 v19, v8, v1
	s_movk_i32 s44, 0x1100
	v_lshlrev_b32_e32 v148, 3, v3
	v_add_u32_e32 v130, -3, v9
	v_lshl_add_u32 v11, v3, 4, s6
	v_add_u32_e32 v152, 0x7d, v9
	v_add_u32_e32 v12, s6, v155
	v_lshl_add_u32 v15, v153, 2, s45
	v_mul_lo_u32 v4, v158, s47
	v_mul_lo_u32 v16, v159, s47
	v_mul_lo_u32 v17, v160, s47
	v_mul_lo_u32 v18, v161, s47
	v_cmp_lt_i32_e64 s[22:23], -2, v9
	v_cmp_lt_i32_e64 s[24:25], -3, v9
	v_mul_lo_u32 v9, v9, s47
	v_mul_lo_u32 v7, v7, s47
	v_mul_u32_u24_e32 v3, 0x110, v3
	v_lshl_add_u32 v204, v20, 2, s46
	v_lshl_add_u32 v206, v19, 2, s46
	v_lshl_add_u32 v207, v8, 2, v14
	v_mul_lo_u32 v8, v144, s44
	v_mul_lo_u32 v5, v5, s47
	v_mul_lo_u32 v19, v134, s47
	v_mul_lo_u32 v20, v136, s47
	v_cmp_gt_i32_e64 s[4:5], 64, v126
	v_or_b32_e32 v149, 0x400, v148
	v_or_b32_e32 v150, 0x1000, v148
	v_ashrrev_i32_e32 v131, 31, v130
	v_add_u32_e32 v151, s64, v10
	v_cmp_lt_i32_e64 s[6:7], 0, v144
	v_cmp_eq_u32_e64 s[8:9], 7, v144
	v_ashrrev_i32_e32 v127, 31, v126
	v_cmp_gt_i32_e64 s[10:11], 64, v158
	v_cmp_gt_i32_e64 s[12:13], 64, v159
	v_cmp_gt_i32_e64 s[14:15], 64, v160
	v_cmp_gt_i32_e64 s[16:17], 64, v161
	v_ashrrev_i32_e32 v135, 31, v134
	v_ashrrev_i32_e32 v137, 31, v136
	v_lshl_add_u32 v208, v13, 1, v154
	v_add_u32_e32 v209, s40, v10
	v_add_u32_e32 v210, v6, v4
	v_add_u32_e32 v211, v6, v16
	v_add_u32_e32 v212, v6, v17
	v_add_u32_e32 v213, v6, v18
	s_mov_b64 s[44:45], 0x1000
	s_mov_b64 s[46:47], 0x2000
	s_mov_b64 s[48:49], 0x3000
	v_add_u32_e32 v214, v11, v9
	v_add_u32_e32 v215, v11, v7
	v_add_u32_e32 v216, v12, v3
	s_mov_b32 s65, 0xbecccccd
	v_mov_b32_e32 v217, 0x3c088889
	v_add_u32_e32 v218, v14, v8
	v_add_u32_e32 v219, v14, v5
	v_add_u32_e32 v220, v15, v19
	v_add_u32_e32 v221, v15, v20
	s_mov_b32 s66, s33
	s_branch .LBB0_3836

; #define SUB(k, bit) (!(kargs()->li == 1 && (k) == lo) || ((kargs()->submask >> (bit)) & 1u))
; __global__ void __launch_bounds__(NWAVES * 64, 2) fwd(Args args_unused) {
;     ...
;             if (SUB(pb + 5, 1))
;             for (int row0 = gw; row0 < M; row0 += 2 * NGW) {
;                 const int hh = lane >> 3;
;                 float l0[2], l1[2], l2[2]; v4u r0[2], r1[2], r2[2], yr[2][2], zr[2][2];
; #pragma unroll
;                 for (int k = 0; k < 2; ++k) { const int row = row0 + k * NGW;
;                     l0[k] = 0.f; l1[k] = 0.f; l2[k] = 0.f; r0[k] = (v4u){0u, 0u, 0u, 0u}; r1[k] = (v4u){0u, 0u, 0u, 0u}; r2[k] = (v4u){0u, 0u, 0u, 0u};
; #pragma unroll
;                     for (int q = 0; q < 2; ++q) { yr[k][q] = (v4u){0u, 0u, 0u, 0u}; zr[k][q] = (v4u){0u, 0u, 0u, 0u}; }
;                     if (row < M) {
;                         l0[k] = LSE[((size_t)0 * M + row) * 8 + hh]; l1[k] = LSE[((size_t)1 * M + row) * 8 + hh]; l2[k] = LSE[((size_t)2 * M + row) * 8 + hh];
;                         r0[k] = *(const v4u*)(OG + ((size_t)0 * M + row) * 512 + 8 * lane); r1[k] = *(const v4u*)(OG + ((size_t)1 * M + row) * 512 + 8 * lane); r2[k] = *(const v4u*)(OG + ((size_t)2 * M + row) * 512 + 8 * lane);
; #pragma unroll
;                         for (int q = 0; q < 2; ++q) { const int col = q * 512 + 8 * lane; yr[k][q] = *(const v4u*)(YS + (size_t)row * DM + col); zr[k][q] = *(const v4u*)ZP(Z, row, ZZB + col); } } }
.Lro_p8_3:
	s_lshl_b32 s4, s33, 3
	s_add_i32 s4, s4, s62
	s_cmp_gt_i32 s4, 0x80ff
	s_cbranch_scc1 .LBB0_3954
	s_load_dwordx2 s[6:7], s[34:35], 0xc8
	v_lshlrev_b32_e32 v74, 5, v1
	v_mov_b32_e32 v75, 0
	s_mov_b64 s[8:9], 0x1000
	s_mov_b32 s5, 0x8100
	s_waitcnt lgkmcnt(0)
	v_lshl_add_u64 v[2:3], s[6:7], 0, v[74:75]
	v_lshl_add_u64 v[18:19], v[2:3], 0, s[8:9]
	v_add_co_u32_e32 v20, vcc, 0x1000, v2
	s_mov_b64 s[6:7], 0xb800000
	s_nop 0
	v_addc_co_u32_e32 v21, vcc, 0, v3, vcc
	global_load_dwordx4 v[2:5], v[18:19], off offset:16
	global_load_dwordx4 v[6:9], v[18:19], off offset:2048
	global_load_dwordx4 v[10:13], v[20:21], off
	global_load_dwordx4 v[14:17], v[18:19], off offset:2064
	v_lshrrev_b32_e32 v18, 1, v1
	v_and_b32_e32 v74, 28, v18
	v_lshl_add_u64 v[18:19], s[30:31], 0, v[74:75]
	v_lshlrev_b32_e32 v74, 4, v1
	v_lshl_add_u64 v[76:77], v[18:19], 0, s[6:7]
	v_lshl_add_u64 v[18:19], s[30:31], 0, v[74:75]
	s_mov_b64 s[6:7], 0x67c00000
	v_lshl_add_u64 v[78:79], v[18:19], 0, s[6:7]
	s_mov_b64 s[6:7], 0x75e00000
	v_lshl_add_u64 v[82:83], v[18:19], 0, s[6:7]
	s_mov_b64 s[6:7], 0x6dd00000
	v_and_b32_e32 v74, 0x1f0, v74
	v_lshrrev_b32_e32 v1, 5, v1
	v_mov_b32_e32 v20, 0x91200
	v_lshl_add_u64 v[86:87], v[18:19], 0, s[6:7]
	s_mov_b64 s[6:7], 0x5fb00000
	v_lshl_add_u64 v[80:81], s[26:27], 0, v[74:75]
	v_mad_u32_u24 v74, v1, s5, v20
	v_mov_b32_e32 v20, 0xa1400
	v_lshl_add_u64 v[88:89], v[18:19], 0, s[6:7]
	v_mbcnt_lo_u32_b32 v18, -1, 0
	s_lshl_b32 s12, s3, 3
	v_mad_u32_u24 v84, v1, s5, v20
	v_mov_b32_e32 v85, v75
	s_lshl_b32 s3, s3, 4
	v_mov_b32_e32 v1, 0x358637bd
	v_mbcnt_hi_u32_b32 v90, -1, v18
	s_branch .LBB0_3950

; __global__ void __launch_bounds__(NWAVES * 64, 2) fwd(Args args_unused) {
	.amdhsa_kernel _Z3fwd4Args
		.amdhsa_group_segment_fixed_size 0
		.amdhsa_private_segment_fixed_size 0
		.amdhsa_kernarg_size 616
		.amdhsa_user_sgpr_count 2
		.amdhsa_user_sgpr_dispatch_ptr 0
		.amdhsa_user_sgpr_queue_ptr 0
		.amdhsa_user_sgpr_kernarg_segment_ptr 1
		.amdhsa_user_sgpr_dispatch_id 0
		.amdhsa_user_sgpr_kernarg_preload_length 0
		.amdhsa_user_sgpr_kernarg_preload_offset 0
		.amdhsa_user_sgpr_private_segment_size 0
		.amdhsa_uses_dynamic_stack 0
		.amdhsa_enable_private_segment 0
		.amdhsa_system_sgpr_workgroup_id_x 1
		.amdhsa_system_sgpr_workgroup_id_y 0
		.amdhsa_system_sgpr_workgroup_id_z 0
		.amdhsa_system_sgpr_workgroup_info 0
		.amdhsa_system_vgpr_workitem_id 0
		.amdhsa_next_free_vgpr 256
		.amdhsa_next_free_sgpr 102
		.amdhsa_accum_offset 256
		.amdhsa_reserve_vcc 1
		.amdhsa_float_round_mode_32 0
		.amdhsa_float_round_mode_16_64 0
		.amdhsa_float_denorm_mode_32 3
		.amdhsa_float_denorm_mode_16_64 3
		.amdhsa_dx10_clamp 1
		.amdhsa_ieee_mode 1
		.amdhsa_fp16_overflow 0
		.amdhsa_tg_split 0
		.amdhsa_exception_fp_ieee_invalid_op 0
		.amdhsa_exception_fp_denorm_src 0
		.amdhsa_exception_fp_ieee_div_zero 0
		.amdhsa_exception_fp_ieee_overflow 0
		.amdhsa_exception_fp_ieee_underflow 0
		.amdhsa_exception_fp_ieee_inexact 0
		.amdhsa_exception_int_div_zero 0
	.end_amdhsa_kernel
